# code prefetch into L2 also at kernel entry (first 32 KB) and at the last three seams
# baseline (speedup 1.0000x reference)
_Z12trunk_kernel2KP:
	s_getpc_b64 s[18:19]
	v_and_b32_e32 v254, 0x3ff, v0
	v_lshlrev_b32_e32 v254, 6, v254
	global_load_dword v255, v254, s[18:19]
	s_mov_b32 s88, s2
	s_load_dwordx2 s[80:81], s[0:1], 0x120
	s_load_dword s2, s[0:1], 0x12c
	s_load_dwordx2 s[86:87], s[0:1], 0x140
	s_mov_b64 s[92:93], s[0:1]
	s_add_u32 s6, s92, 0x140
	s_addc_u32 s7, s93, 0
	v_and_b32_e32 v174, 0x3ff, v0
	v_cmp_eq_u32_e64 s[8:9], 0, v174
	s_mov_b64 s[4:5], exec
	s_nop 0
	v_writelane_b32 v252, s8, 0
	s_nop 1
	v_writelane_b32 v252, s9, 1
	s_and_b64 s[8:9], s[4:5], s[8:9]
	s_mov_b64 exec, s[8:9]
	s_cbranch_execz .LBB0_2
	v_mov_b32_e32 v1, 0
	v_mov_b32_e32 v2, 0x20000
	ds_write_b32 v2, v1
	v_mov_b32_e32 v2, 0x20004
	ds_write_b32 v2, v1
	v_mov_b32_e32 v2, 0x20008
	ds_write_b32 v2, v1
	v_mov_b32_e32 v2, 0x2000c
	ds_write_b32 v2, v1

.Lxb_pf_14:
	s_getpc_b64 s[18:19]
	s_mov_b64 s[22:23], exec
	s_mov_b64 exec, -1
	v_mbcnt_lo_u32_b32 v254, -1, 0
	v_mbcnt_hi_u32_b32 v254, -1, v254
	v_lshlrev_b32_e32 v254, 7, v254
	global_load_dword v255, v254, s[18:19]
	s_mov_b64 exec, s[22:23]
